# attention work queue: the fetch-add for the next item is issued at the start of the previous item's epilogue instead of between items
# speedup vs baseline: 1.0296x; 1.0019x over previous
.LBB0_40:
	s_andn2_b64 vcc, exec, s[0:1]
	s_cbranch_vccnz .LBB0_88
	s_cmp_gt_i32 s38, 9
	s_mov_b64 s[0:1], -1
	s_cbranch_scc0 .LBB0_60
	v_readfirstlane_b32 s2, v184
	v_readfirstlane_b32 s3, v185
	s_waitcnt vmcnt(1)
	v_mov_b32_e32 v8, v189
	v_mov_b32_e32 v197, v187
	v_bfe_u32 v9, v8, 5, 1
	v_ashrrev_i32_e32 v0, 3, v8
	v_ashrrev_i32_e32 v1, 1, v8
	v_lshlrev_b32_e32 v196, 4, v9
	s_add_u32 s8, s2, 0xb000000
	v_and_b32_e32 v193, 0xffffffe0, v1
	v_lshl_add_u64 v[2:3], s[2:3], 0, v[196:197]
	s_mov_b64 s[6:7], 0x8000000
	v_ashrrev_i32_e32 v1, 31, v0
	s_addc_u32 s9, s3, 0
	v_ashrrev_i32_e32 v194, 2, v8
	v_and_b32_e32 v4, 7, v8
	v_lshl_add_u64 v[198:199], v[2:3], 0, s[6:7]
	v_lshlrev_b64 v[2:3], 14, v[0:1]
	s_add_u32 s4, s2, 0x1000000
	v_lshl_add_u64 v[2:3], s[2:3], 0, v[2:3]
	v_lshlrev_b32_e32 v4, 4, v4
	v_mov_b32_e32 v5, v187
	v_ashrrev_i32_e32 v195, 31, v194
	s_addc_u32 s5, s3, 0
	v_and_b32_e32 v6, 3, v8
	v_lshl_add_u64 v[2:3], v[2:3], 0, v[4:5]
	s_mov_b64 s[6:7], 0xd000000
	v_lshlrev_b64 v[4:5], 7, v[194:195]
	v_lshl_add_u64 v[200:201], v[2:3], 0, s[6:7]
	v_lshlrev_b32_e32 v2, 3, v6
	v_lshl_add_u64 v[4:5], s[4:5], 0, v[4:5]
	v_lshlrev_b32_e32 v6, 4, v6
	v_mov_b32_e32 v7, v187
	s_movk_i32 s6, 0x190
	v_lshlrev_b32_e32 v1, 4, v8
	v_and_b32_e32 v192, 31, v8
	v_lshl_add_u64 v[204:205], v[4:5], 0, v[6:7]
	v_mul_lo_u32 v3, v194, s6
	v_and_b32_e32 v4, 0x60, v1
	s_movk_i32 s6, 0x90
	s_add_u32 s0, s2, 0x1400000
	v_lshlrev_b32_e32 v186, 3, v9
	v_lshlrev_b64 v[202:203], 8, v[194:195]
	v_mad_u64_u32 v[0:1], s[6:7], v0, s6, v[4:5]
	v_mul_u32_u24_e32 v195, 0x190, v192
	v_lshlrev_b32_e32 v4, 8, v192
	s_addc_u32 s1, s3, 0
	v_lshlrev_b32_e32 v1, 3, v8
	v_lshl_add_u64 v[206:207], s[4:5], 0, v[6:7]
	v_sub_u32_e32 v7, v195, v4
	v_lshl_add_u64 v[4:5], s[2:3], 0, v[186:187]
	s_mov_b64 s[2:3], 0x6000000
	v_and_b32_e32 v1, 8, v1
	v_lshl_add_u64 v[208:209], v[4:5], 0, s[2:3]
	s_mov_b64 s[2:3], 0x4000000
	v_cmp_eq_u32_e64 s[10:11], 0, v8
	v_lshlrev_b32_e32 v197, 2, v9
	v_lshl_add_u64 v[210:211], v[4:5], 0, s[2:3]
	v_lshlrev_b32_e32 v186, 1, v2
	v_add_u32_e32 v237, v3, v6
	v_add_u32_e32 v238, v0, v1
	v_add_u32_e32 v239, v7, v196
	s_mov_b32 s101, 0
	s_branch .LBB0_45
.LBB0_43:
	v_ashrrev_i32_e32 v69, 31, v214
	v_mov_b32_e32 v68, v214
	v_lshlrev_b64 v[68:69], 12, v[68:69]
	v_lshl_or_b32 v68, s6, 8, v68
	v_lshl_add_u64 v[66:67], v[208:209], 0, v[68:69]
	v_lshl_add_u64 v[68:69], v[210:211], 0, v[68:69]
	global_load_dwordx2 v[144:145], v[66:67], off
	global_load_dwordx2 v[146:147], v[66:67], off offset:16
	global_load_dwordx2 v[148:149], v[66:67], off offset:32
	global_load_dwordx2 v[150:151], v[66:67], off offset:48
	global_load_dwordx2 v[152:153], v[66:67], off offset:64
	global_load_dwordx2 v[154:155], v[66:67], off offset:80
	global_load_dwordx2 v[156:157], v[66:67], off offset:96
	global_load_dwordx2 v[158:159], v[66:67], off offset:112
	global_load_dwordx2 v[160:161], v[66:67], off offset:128
	global_load_dwordx2 v[162:163], v[66:67], off offset:144
	global_load_dwordx2 v[164:165], v[66:67], off offset:160
	global_load_dwordx2 v[166:167], v[66:67], off offset:176
	global_load_dwordx2 v[168:169], v[66:67], off offset:192
	global_load_dwordx2 v[170:171], v[66:67], off offset:208
	global_load_dwordx2 v[172:173], v[66:67], off offset:224
	global_load_dwordx2 v[174:175], v[66:67], off offset:240
	s_and_saveexec_b64 s[4:5], s[10:11]
	s_cbranch_execz .Lq_noissue
	v_mov_b32_e32 v80, 1
	global_atomic_add v80, v187, v80, s[0:1] sc0
.Lq_noissue:
	s_or_b64 exec, exec, s[4:5]
	s_mov_b32 s101, 1
	v_cmp_lt_i32_e32 vcc, v228, v227
	s_nop 1
	v_cndmask_b32_e32 v64, v226, v228, vcc
	v_lshlrev_b32_e32 v64, 2, v64
	ds_bpermute_b32 v64, v64, v215
	s_waitcnt lgkmcnt(0)
	v_add_f32_e32 v64, v215, v64
	v_div_scale_f32 v65, s[2:3], v64, v64, 1.0
	v_rcp_f32_e32 v66, v65
	s_nop 1
	v_fma_f32 v67, -v65, v66, 1.0
	s_mov_b64 s[2:3], 0
	v_fmac_f32_e32 v66, v67, v66
	v_div_scale_f32 v67, vcc, 1.0, v64, 1.0
	v_mul_f32_e32 v78, v67, v66
	v_fma_f32 v79, -v65, v78, v67
	v_fmac_f32_e32 v78, v79, v66
	v_fma_f32 v65, -v65, v78, v67
	v_div_fmas_f32 v65, v65, v66, v78
	v_div_fixup_f32 v64, v65, v64, 1.0
	v_pk_mul_f32 v[48:49], v[48:49], v[64:65] op_sel_hi:[1,0]
	v_pk_mul_f32 v[50:51], v[50:51], v[64:65] op_sel_hi:[1,0]
	s_waitcnt vmcnt(15)
	v_lshlrev_b32_e32 v72, 16, v144
	v_and_b32_e32 v73, 0xffff0000, v144
	v_lshlrev_b32_e32 v74, 16, v145
	v_and_b32_e32 v75, 0xffff0000, v145
	v_pk_mul_f32 v[48:49], v[48:49], v[72:73]
	v_pk_mul_f32 v[50:51], v[50:51], v[74:75]
	v_cvt_pk_bf16_f32 v70, v48, v49
	v_cvt_pk_bf16_f32 v71, v50, v51
	global_store_dwordx2 v[68:69], v[70:71], off
	v_pk_mul_f32 v[52:53], v[52:53], v[64:65] op_sel_hi:[1,0]
	v_pk_mul_f32 v[54:55], v[54:55], v[64:65] op_sel_hi:[1,0]
	s_waitcnt vmcnt(15)
	v_lshlrev_b32_e32 v72, 16, v146
	v_and_b32_e32 v73, 0xffff0000, v146
	v_lshlrev_b32_e32 v74, 16, v147
	v_and_b32_e32 v75, 0xffff0000, v147
	v_pk_mul_f32 v[52:53], v[52:53], v[72:73]
	v_pk_mul_f32 v[54:55], v[54:55], v[74:75]
	v_cvt_pk_bf16_f32 v76, v52, v53
	v_cvt_pk_bf16_f32 v77, v54, v55
	global_store_dwordx2 v[68:69], v[76:77], off offset:16
	v_pk_mul_f32 v[56:57], v[56:57], v[64:65] op_sel_hi:[1,0]
	v_pk_mul_f32 v[58:59], v[58:59], v[64:65] op_sel_hi:[1,0]
	s_waitcnt vmcnt(15)
	v_lshlrev_b32_e32 v72, 16, v148
	v_and_b32_e32 v73, 0xffff0000, v148
	v_lshlrev_b32_e32 v74, 16, v149
	v_and_b32_e32 v75, 0xffff0000, v149
	v_pk_mul_f32 v[56:57], v[56:57], v[72:73]
	v_pk_mul_f32 v[58:59], v[58:59], v[74:75]
	v_cvt_pk_bf16_f32 v70, v56, v57
	v_cvt_pk_bf16_f32 v71, v58, v59
	global_store_dwordx2 v[68:69], v[70:71], off offset:32
	v_pk_mul_f32 v[60:61], v[60:61], v[64:65] op_sel_hi:[1,0]
	v_pk_mul_f32 v[62:63], v[62:63], v[64:65] op_sel_hi:[1,0]
	s_waitcnt vmcnt(15)
	v_lshlrev_b32_e32 v72, 16, v150
	v_and_b32_e32 v73, 0xffff0000, v150
	v_lshlrev_b32_e32 v74, 16, v151
	v_and_b32_e32 v75, 0xffff0000, v151
	v_pk_mul_f32 v[60:61], v[60:61], v[72:73]
	v_pk_mul_f32 v[62:63], v[62:63], v[74:75]
	v_cvt_pk_bf16_f32 v76, v60, v61
	v_cvt_pk_bf16_f32 v77, v62, v63
	global_store_dwordx2 v[68:69], v[76:77], off offset:48
	v_pk_mul_f32 v[32:33], v[32:33], v[64:65] op_sel_hi:[1,0]
	v_pk_mul_f32 v[34:35], v[34:35], v[64:65] op_sel_hi:[1,0]
	s_waitcnt vmcnt(15)
	v_lshlrev_b32_e32 v72, 16, v152
	v_and_b32_e32 v73, 0xffff0000, v152
	v_lshlrev_b32_e32 v74, 16, v153
	v_and_b32_e32 v75, 0xffff0000, v153
	v_pk_mul_f32 v[32:33], v[32:33], v[72:73]
	v_pk_mul_f32 v[34:35], v[34:35], v[74:75]
	v_cvt_pk_bf16_f32 v70, v32, v33
	v_cvt_pk_bf16_f32 v71, v34, v35
	global_store_dwordx2 v[68:69], v[70:71], off offset:64
	v_pk_mul_f32 v[36:37], v[36:37], v[64:65] op_sel_hi:[1,0]
	v_pk_mul_f32 v[38:39], v[38:39], v[64:65] op_sel_hi:[1,0]
	s_waitcnt vmcnt(15)
	v_lshlrev_b32_e32 v72, 16, v154
	v_and_b32_e32 v73, 0xffff0000, v154
	v_lshlrev_b32_e32 v74, 16, v155
	v_and_b32_e32 v75, 0xffff0000, v155
	v_pk_mul_f32 v[36:37], v[36:37], v[72:73]
	v_pk_mul_f32 v[38:39], v[38:39], v[74:75]
	v_cvt_pk_bf16_f32 v76, v36, v37
	v_cvt_pk_bf16_f32 v77, v38, v39
	global_store_dwordx2 v[68:69], v[76:77], off offset:80
	v_pk_mul_f32 v[40:41], v[40:41], v[64:65] op_sel_hi:[1,0]
	v_pk_mul_f32 v[42:43], v[42:43], v[64:65] op_sel_hi:[1,0]
	s_waitcnt vmcnt(15)
	v_lshlrev_b32_e32 v72, 16, v156
	v_and_b32_e32 v73, 0xffff0000, v156
	v_lshlrev_b32_e32 v74, 16, v157
	v_and_b32_e32 v75, 0xffff0000, v157
	v_pk_mul_f32 v[40:41], v[40:41], v[72:73]
	v_pk_mul_f32 v[42:43], v[42:43], v[74:75]
	v_cvt_pk_bf16_f32 v70, v40, v41
	v_cvt_pk_bf16_f32 v71, v42, v43
	global_store_dwordx2 v[68:69], v[70:71], off offset:96
	v_pk_mul_f32 v[44:45], v[44:45], v[64:65] op_sel_hi:[1,0]
	v_pk_mul_f32 v[46:47], v[46:47], v[64:65] op_sel_hi:[1,0]
	s_waitcnt vmcnt(15)
	v_lshlrev_b32_e32 v72, 16, v158
	v_and_b32_e32 v73, 0xffff0000, v158
	v_lshlrev_b32_e32 v74, 16, v159
	v_and_b32_e32 v75, 0xffff0000, v159
	v_pk_mul_f32 v[44:45], v[44:45], v[72:73]
	v_pk_mul_f32 v[46:47], v[46:47], v[74:75]
	v_cvt_pk_bf16_f32 v76, v44, v45
	v_cvt_pk_bf16_f32 v77, v46, v47
	global_store_dwordx2 v[68:69], v[76:77], off offset:112
	v_pk_mul_f32 v[16:17], v[16:17], v[64:65] op_sel_hi:[1,0]
	v_pk_mul_f32 v[18:19], v[18:19], v[64:65] op_sel_hi:[1,0]
	s_waitcnt vmcnt(15)
	v_lshlrev_b32_e32 v72, 16, v160
	v_and_b32_e32 v73, 0xffff0000, v160
	v_lshlrev_b32_e32 v74, 16, v161
	v_and_b32_e32 v75, 0xffff0000, v161
	v_pk_mul_f32 v[16:17], v[16:17], v[72:73]
	v_pk_mul_f32 v[18:19], v[18:19], v[74:75]
	v_cvt_pk_bf16_f32 v70, v16, v17
	v_cvt_pk_bf16_f32 v71, v18, v19
	global_store_dwordx2 v[68:69], v[70:71], off offset:128
	v_pk_mul_f32 v[20:21], v[20:21], v[64:65] op_sel_hi:[1,0]
	v_pk_mul_f32 v[22:23], v[22:23], v[64:65] op_sel_hi:[1,0]
	s_waitcnt vmcnt(15)
	v_lshlrev_b32_e32 v72, 16, v162
	v_and_b32_e32 v73, 0xffff0000, v162
	v_lshlrev_b32_e32 v74, 16, v163
	v_and_b32_e32 v75, 0xffff0000, v163
	v_pk_mul_f32 v[20:21], v[20:21], v[72:73]
	v_pk_mul_f32 v[22:23], v[22:23], v[74:75]
	v_cvt_pk_bf16_f32 v76, v20, v21
	v_cvt_pk_bf16_f32 v77, v22, v23
	global_store_dwordx2 v[68:69], v[76:77], off offset:144
	v_pk_mul_f32 v[24:25], v[24:25], v[64:65] op_sel_hi:[1,0]
	v_pk_mul_f32 v[26:27], v[26:27], v[64:65] op_sel_hi:[1,0]
	s_waitcnt vmcnt(15)
	v_lshlrev_b32_e32 v72, 16, v164
	v_and_b32_e32 v73, 0xffff0000, v164
	v_lshlrev_b32_e32 v74, 16, v165
	v_and_b32_e32 v75, 0xffff0000, v165
	v_pk_mul_f32 v[24:25], v[24:25], v[72:73]
	v_pk_mul_f32 v[26:27], v[26:27], v[74:75]
	v_cvt_pk_bf16_f32 v70, v24, v25
	v_cvt_pk_bf16_f32 v71, v26, v27
	global_store_dwordx2 v[68:69], v[70:71], off offset:160
	v_pk_mul_f32 v[28:29], v[28:29], v[64:65] op_sel_hi:[1,0]
	v_pk_mul_f32 v[30:31], v[30:31], v[64:65] op_sel_hi:[1,0]
	s_waitcnt vmcnt(15)
	v_lshlrev_b32_e32 v72, 16, v166
	v_and_b32_e32 v73, 0xffff0000, v166
	v_lshlrev_b32_e32 v74, 16, v167
	v_and_b32_e32 v75, 0xffff0000, v167
	v_pk_mul_f32 v[28:29], v[28:29], v[72:73]
	v_pk_mul_f32 v[30:31], v[30:31], v[74:75]
	v_cvt_pk_bf16_f32 v76, v28, v29
	v_cvt_pk_bf16_f32 v77, v30, v31
	global_store_dwordx2 v[68:69], v[76:77], off offset:176
	v_pk_mul_f32 v[0:1], v[0:1], v[64:65] op_sel_hi:[1,0]
	v_pk_mul_f32 v[2:3], v[2:3], v[64:65] op_sel_hi:[1,0]
	s_waitcnt vmcnt(15)
	v_lshlrev_b32_e32 v72, 16, v168
	v_and_b32_e32 v73, 0xffff0000, v168
	v_lshlrev_b32_e32 v74, 16, v169
	v_and_b32_e32 v75, 0xffff0000, v169
	v_pk_mul_f32 v[0:1], v[0:1], v[72:73]
	v_pk_mul_f32 v[2:3], v[2:3], v[74:75]
	v_cvt_pk_bf16_f32 v70, v0, v1
	v_cvt_pk_bf16_f32 v71, v2, v3
	global_store_dwordx2 v[68:69], v[70:71], off offset:192
	v_pk_mul_f32 v[4:5], v[4:5], v[64:65] op_sel_hi:[1,0]
	v_pk_mul_f32 v[6:7], v[6:7], v[64:65] op_sel_hi:[1,0]
	s_waitcnt vmcnt(15)
	v_lshlrev_b32_e32 v72, 16, v170
	v_and_b32_e32 v73, 0xffff0000, v170
	v_lshlrev_b32_e32 v74, 16, v171
	v_and_b32_e32 v75, 0xffff0000, v171
	v_pk_mul_f32 v[4:5], v[4:5], v[72:73]
	v_pk_mul_f32 v[6:7], v[6:7], v[74:75]
	v_cvt_pk_bf16_f32 v76, v4, v5
	v_cvt_pk_bf16_f32 v77, v6, v7
	global_store_dwordx2 v[68:69], v[76:77], off offset:208
	v_pk_mul_f32 v[8:9], v[8:9], v[64:65] op_sel_hi:[1,0]
	v_pk_mul_f32 v[10:11], v[10:11], v[64:65] op_sel_hi:[1,0]
	s_waitcnt vmcnt(15)
	v_lshlrev_b32_e32 v72, 16, v172
	v_and_b32_e32 v73, 0xffff0000, v172
	v_lshlrev_b32_e32 v74, 16, v173
	v_and_b32_e32 v75, 0xffff0000, v173
	v_pk_mul_f32 v[8:9], v[8:9], v[72:73]
	v_pk_mul_f32 v[10:11], v[10:11], v[74:75]
	v_cvt_pk_bf16_f32 v70, v8, v9
	v_cvt_pk_bf16_f32 v71, v10, v11
	global_store_dwordx2 v[68:69], v[70:71], off offset:224
	v_pk_mul_f32 v[12:13], v[12:13], v[64:65] op_sel_hi:[1,0]
	v_pk_mul_f32 v[14:15], v[14:15], v[64:65] op_sel_hi:[1,0]
	s_waitcnt vmcnt(15)
	v_lshlrev_b32_e32 v72, 16, v174
	v_and_b32_e32 v73, 0xffff0000, v174
	v_lshlrev_b32_e32 v74, 16, v175
	v_and_b32_e32 v75, 0xffff0000, v175
	v_pk_mul_f32 v[12:13], v[12:13], v[72:73]
	v_pk_mul_f32 v[14:15], v[14:15], v[74:75]
	v_cvt_pk_bf16_f32 v76, v12, v13
	v_cvt_pk_bf16_f32 v77, v14, v15
	global_store_dwordx2 v[68:69], v[76:77], off offset:240

.LBB0_45:
	s_waitcnt vmcnt(63) expcnt(7) lgkmcnt(15)
	s_barrier
	s_and_saveexec_b64 s[2:3], s[10:11]
	s_cbranch_execz .LBB0_49
	s_mov_b64 s[6:7], exec
	v_mbcnt_lo_u32_b32 v0, s6, 0
	v_mbcnt_hi_u32_b32 v0, s7, v0
	v_cmp_eq_u32_e32 vcc, 0, v0
	s_and_saveexec_b64 s[4:5], vcc
	s_cbranch_execz .LBB0_48
	s_cmp_eq_u32 s101, 1
	s_cbranch_scc1 .Lq_have
	s_bcnt1_i32_b64 s6, s[6:7]
	v_mov_b32_e32 v1, s6
	global_atomic_add v1, v187, v1, s[0:1] sc0
	s_branch .LBB0_48
.Lq_have:
	s_waitcnt vmcnt(0)
	v_mov_b32_e32 v1, v80
.LBB0_48:
	s_or_b64 exec, exec, s[4:5]
	s_mov_b32 s101, 0
	s_waitcnt vmcnt(0)
	v_readfirstlane_b32 s4, v1
	s_nop 1
	v_add_u32_e32 v0, s4, v0
	ds_write_b32 v187, v0 offset:44032
